# gemm256 K-loop reschedule (4 sites) + P9 softmax fast path: 4 rows per batch, interleaved reductions, loads one batch ahead
# speedup vs baseline: 1.0283x; 1.0049x over previous
; DEV void store_bf4(bf16_t* p, f32x4 v) { uint2 w; w.x = cvt_pk_bf16(v[0], v[1]); w.y = cvt_pk_bf16(v[2], v[3]); *(uint2*)p = w; }
; DEV float wave_max(float v) {
; #pragma unroll
;     for (int o = 32; o >= 1; o >>= 1) v = fmaxf(v, __shfl_xor(v, o));
;     return v;
; }
; __global__ void __launch_bounds__(512) hymba_fwd(Params p) {
;     ...
;     for (int r = bid * 8 + wid; r < TP * 4; r += G * 8) {
;         const f32x4 v = __builtin_nontemporal_load((const f32x4*)(sc + (size_t)r * 256 + lane * 4));
;         const float mx = wave_max(fmaxf(fmaxf(v[0], v[1]), fmaxf(v[2], v[3])));
;         f32x4 e; e[0] = __expf(v[0] - mx); e[1] = __expf(v[1] - mx); e[2] = __expf(v[2] - mx); e[3] = __expf(v[3] - mx);
;         const float inv = 1.f / wave_sum(e[0] + e[1] + e[2] + e[3]);
;         store_bf4(pb + (size_t)(r >> 2) * LDP + (r & 3) * 256 + lane * 4, e * inv);
.LBB0_1349:
	s_or_b64 exec, exec, s[4:5]
	s_waitcnt lgkmcnt(0)
	s_barrier
	s_load_dwordx2 s[4:5], s[0:1], 0xd0
	s_mov_b64 s[6:7], 0x20f39000
	v_lshl_add_u64 v[86:87], v[158:159], 0, s[6:7]
	s_waitcnt lgkmcnt(0)
	s_cmp_lt_i32 s4, 10
	s_cselect_b64 s[8:9], -1, 0
	s_cmp_gt_i32 s5, 9
	s_cselect_b64 s[4:5], -1, 0
	s_and_b64 s[4:5], s[8:9], s[4:5]
	s_andn2_b64 vcc, exec, s[4:5]
	s_cbranch_vccnz .LBB0_1354
	v_mov_b32_e32 v2, v0
	s_lshl_b32 s8, s2, 3
	v_ashrrev_i32_e32 v6, 6, v2
	v_add_u32_e32 v1, s8, v6
	s_mov_b32 s4, 0x8000
	v_cmp_gt_i32_e32 vcc, s4, v1
	s_and_saveexec_b64 s[4:5], vcc
	s_cbranch_execz .LBB0_1353
	v_mbcnt_lo_u32_b32 v4, -1, 0
	v_mbcnt_hi_u32_b32 v4, -1, v4
	v_and_b32_e32 v5, 64, v4
	v_add_u32_e32 v5, 64, v5
	v_xor_b32_e32 v7, 32, v4
	v_cmp_lt_i32_e32 vcc, v7, v5
	s_ashr_i32 s9, s8, 31
	v_lshlrev_b32_e32 v3, 2, v2
	v_cndmask_b32_e32 v7, v4, v7, vcc
	v_lshlrev_b32_e32 v8, 2, v7
	v_xor_b32_e32 v7, 16, v4
	v_cmp_lt_i32_e32 vcc, v7, v5
	v_and_b32_e32 v2, 63, v2
	s_lshl_b32 s6, s33, 3
	v_cndmask_b32_e32 v7, v4, v7, vcc
	v_lshlrev_b32_e32 v9, 2, v7
	v_xor_b32_e32 v7, 8, v4
	v_cmp_lt_i32_e32 vcc, v7, v5
	v_and_b32_e32 v16, 0xfc, v3
	v_mov_b32_e32 v3, 0
	v_cndmask_b32_e32 v7, v4, v7, vcc
	v_lshlrev_b32_e32 v10, 2, v7
	v_xor_b32_e32 v7, 4, v4
	v_cmp_lt_i32_e32 vcc, v7, v5
	s_ashr_i32 s7, s6, 31
	s_mov_b64 s[10:11], 0
	v_cndmask_b32_e32 v7, v4, v7, vcc
	v_lshlrev_b32_e32 v11, 2, v7
	v_xor_b32_e32 v7, 2, v4
	v_cmp_lt_i32_e32 vcc, v7, v5
	s_movk_i32 s12, 0x880
	s_movk_i32 s13, 0x7fff
	v_cndmask_b32_e32 v7, v4, v7, vcc
	v_lshlrev_b32_e32 v12, 2, v7
	v_xor_b32_e32 v7, 1, v4
	v_cmp_lt_i32_e32 vcc, v7, v5
	s_nop 1
	v_cndmask_b32_e32 v4, v4, v7, vcc
	v_ashrrev_i32_e32 v7, 31, v6
	v_lshlrev_b32_e32 v13, 2, v4
	v_lshl_add_u64 v[4:5], v[6:7], 0, s[8:9]
	v_lshlrev_b64 v[4:5], 10, v[4:5]
	v_lshl_or_b32 v4, v2, 4, v4
	v_lshl_add_u64 v[4:5], v[158:159], 0, v[4:5]
	s_mov_b64 s[8:9], 0x1ef39000
	v_lshlrev_b32_e32 v2, 8, v6
	v_lshl_add_u64 v[4:5], v[4:5], 0, s[8:9]
	s_lshl_b64 s[8:9], s[6:7], 10
	v_lshl_add_u32 v14, s2, 11, v2
	s_lshl_b32 s7, s33, 11
	v_lshlrev_b32_e32 v6, 1, v16
	v_mov_b32_e32 v7, v3
	s_cmpk_lg_i32 s33, 0x100
	s_cbranch_scc1 .LBB0_1352
	v_ashrrev_i32_e32 v2, 2, v1
	v_and_b32_e32 v15, 0x300, v14
	v_mad_i64_i32 v[20:21], s[16:17], v2, s12, v[86:87]
	v_lshlrev_b32_e32 v2, 1, v15
	v_lshl_add_u64 v[20:21], v[20:21], 0, v[2:3]
	v_lshl_add_u64 v[20:21], v[20:21], 0, v[6:7]
	s_mov_b64 s[10:11], 0x110000
	global_load_dwordx4 v[24:27], v[4:5], off nt
	v_lshl_add_u64 v[4:5], v[4:5], 0, s[8:9]
	global_load_dwordx4 v[28:31], v[4:5], off nt
	v_lshl_add_u64 v[4:5], v[4:5], 0, s[8:9]
	global_load_dwordx4 v[32:35], v[4:5], off nt
	v_lshl_add_u64 v[4:5], v[4:5], 0, s[8:9]
	global_load_dwordx4 v[36:39], v[4:5], off nt
	v_lshl_add_u64 v[4:5], v[4:5], 0, s[8:9]
	global_load_dwordx4 v[40:43], v[4:5], off nt
	v_lshl_add_u64 v[4:5], v[4:5], 0, s[8:9]
	global_load_dwordx4 v[44:47], v[4:5], off nt
	v_lshl_add_u64 v[4:5], v[4:5], 0, s[8:9]
	global_load_dwordx4 v[48:51], v[4:5], off nt
	v_lshl_add_u64 v[4:5], v[4:5], 0, s[8:9]
	global_load_dwordx4 v[52:55], v[4:5], off nt
	v_lshl_add_u64 v[4:5], v[4:5], 0, s[8:9]
	s_waitcnt vmcnt(4)
	v_max_f32_e32 v56, v27, v27
	v_max_f32_e32 v60, v26, v26
	v_max_f32_e32 v56, v60, v56
	v_max3_f32 v56, v24, v25, v56
	v_max_f32_e32 v57, v31, v31
	v_max_f32_e32 v61, v30, v30
	v_max_f32_e32 v57, v61, v57
	v_max3_f32 v57, v28, v29, v57
	v_max_f32_e32 v58, v35, v35
	v_max_f32_e32 v62, v34, v34
	v_max_f32_e32 v58, v62, v58
	v_max3_f32 v58, v32, v33, v58
	v_max_f32_e32 v59, v39, v39
	v_max_f32_e32 v63, v38, v38
	v_max_f32_e32 v59, v63, v59
	v_max3_f32 v59, v36, v37, v59
	ds_bpermute_b32 v60, v8, v56
	ds_bpermute_b32 v61, v8, v57
	ds_bpermute_b32 v62, v8, v58
	ds_bpermute_b32 v63, v8, v59
	s_waitcnt lgkmcnt(3)
	v_max_f32_e32 v60, v60, v60
	v_max_f32_e32 v56, v56, v60
	s_waitcnt lgkmcnt(2)
	v_max_f32_e32 v61, v61, v61
	v_max_f32_e32 v57, v57, v61
	s_waitcnt lgkmcnt(1)
	v_max_f32_e32 v62, v62, v62
	v_max_f32_e32 v58, v58, v62
	s_waitcnt lgkmcnt(0)
	v_max_f32_e32 v63, v63, v63
	v_max_f32_e32 v59, v59, v63
	ds_bpermute_b32 v60, v9, v56
	ds_bpermute_b32 v61, v9, v57
	ds_bpermute_b32 v62, v9, v58
	ds_bpermute_b32 v63, v9, v59
	s_waitcnt lgkmcnt(3)
	v_max_f32_e32 v60, v60, v60
	v_max_f32_e32 v56, v56, v60
	s_waitcnt lgkmcnt(2)
	v_max_f32_e32 v61, v61, v61
	v_max_f32_e32 v57, v57, v61
	s_waitcnt lgkmcnt(1)
	v_max_f32_e32 v62, v62, v62
	v_max_f32_e32 v58, v58, v62
	s_waitcnt lgkmcnt(0)
	v_max_f32_e32 v63, v63, v63
	v_max_f32_e32 v59, v59, v63
	ds_bpermute_b32 v60, v10, v56
	ds_bpermute_b32 v61, v10, v57
	ds_bpermute_b32 v62, v10, v58
	ds_bpermute_b32 v63, v10, v59
	s_waitcnt lgkmcnt(3)
	v_max_f32_e32 v60, v60, v60
	v_max_f32_e32 v56, v56, v60
	s_waitcnt lgkmcnt(2)
	v_max_f32_e32 v61, v61, v61
	v_max_f32_e32 v57, v57, v61
	s_waitcnt lgkmcnt(1)
	v_max_f32_e32 v62, v62, v62
	v_max_f32_e32 v58, v58, v62
	s_waitcnt lgkmcnt(0)
	v_max_f32_e32 v63, v63, v63
	v_max_f32_e32 v59, v59, v63
	ds_bpermute_b32 v60, v11, v56
	ds_bpermute_b32 v61, v11, v57
	ds_bpermute_b32 v62, v11, v58
	ds_bpermute_b32 v63, v11, v59
	s_waitcnt lgkmcnt(3)
	v_max_f32_e32 v60, v60, v60
	v_max_f32_e32 v56, v56, v60
	s_waitcnt lgkmcnt(2)
	v_max_f32_e32 v61, v61, v61
	v_max_f32_e32 v57, v57, v61
	s_waitcnt lgkmcnt(1)
	v_max_f32_e32 v62, v62, v62
	v_max_f32_e32 v58, v58, v62
	s_waitcnt lgkmcnt(0)
	v_max_f32_e32 v63, v63, v63
	v_max_f32_e32 v59, v59, v63
	ds_bpermute_b32 v60, v12, v56
	ds_bpermute_b32 v61, v12, v57
	ds_bpermute_b32 v62, v12, v58
	ds_bpermute_b32 v63, v12, v59
	s_waitcnt lgkmcnt(3)
	v_max_f32_e32 v60, v60, v60
	v_max_f32_e32 v56, v56, v60
	s_waitcnt lgkmcnt(2)
; DEV void store_bf4(bf16_t* p, f32x4 v) { uint2 w; w.x = cvt_pk_bf16(v[0], v[1]); w.y = cvt_pk_bf16(v[2], v[3]); *(uint2*)p = w; }
; DEV float wave_sum(float v) {
; #pragma unroll
;     for (int o = 32; o >= 1; o >>= 1) v += __shfl_xor(v, o);
;     return v;
; }
; DEV float wave_max(float v) {
; #pragma unroll
;     for (int o = 32; o >= 1; o >>= 1) v = fmaxf(v, __shfl_xor(v, o));
;     return v;
; }
; __global__ void __launch_bounds__(512) hymba_fwd(Params p) {
;     ...
;     for (int r = bid * 8 + wid; r < TP * 4; r += G * 8) {
;         const f32x4 v = __builtin_nontemporal_load((const f32x4*)(sc + (size_t)r * 256 + lane * 4));
;         const float mx = wave_max(fmaxf(fmaxf(v[0], v[1]), fmaxf(v[2], v[3])));
;         f32x4 e; e[0] = __expf(v[0] - mx); e[1] = __expf(v[1] - mx); e[2] = __expf(v[2] - mx); e[3] = __expf(v[3] - mx);
;         const float inv = 1.f / wave_sum(e[0] + e[1] + e[2] + e[3]);
;         store_bf4(pb + (size_t)(r >> 2) * LDP + (r & 3) * 256 + lane * 4, e * inv);
	v_max_f32_e32 v61, v61, v61
	v_max_f32_e32 v57, v57, v61
	s_waitcnt lgkmcnt(1)
	v_max_f32_e32 v62, v62, v62
	v_max_f32_e32 v58, v58, v62
	s_waitcnt lgkmcnt(0)
	v_max_f32_e32 v63, v63, v63
	v_max_f32_e32 v59, v59, v63
	ds_bpermute_b32 v60, v13, v56
	ds_bpermute_b32 v61, v13, v57
	ds_bpermute_b32 v62, v13, v58
	ds_bpermute_b32 v63, v13, v59
	s_waitcnt lgkmcnt(3)
	v_max_f32_e32 v60, v60, v60
	v_max_f32_e32 v56, v56, v60
	s_waitcnt lgkmcnt(2)
	v_max_f32_e32 v61, v61, v61
	v_max_f32_e32 v57, v57, v61
	s_waitcnt lgkmcnt(1)
	v_max_f32_e32 v62, v62, v62
	v_max_f32_e32 v58, v58, v62
	s_waitcnt lgkmcnt(0)
	v_max_f32_e32 v63, v63, v63
	v_max_f32_e32 v59, v59, v63
	v_sub_f32_e32 v24, v24, v56
	v_sub_f32_e32 v25, v25, v56
	v_sub_f32_e32 v26, v26, v56
	v_sub_f32_e32 v27, v27, v56
	v_mul_f32_e32 v24, 0x3fb8aa3b, v24
	v_mul_f32_e32 v25, 0x3fb8aa3b, v25
	v_mul_f32_e32 v26, 0x3fb8aa3b, v26
	v_mul_f32_e32 v27, 0x3fb8aa3b, v27
	v_sub_f32_e32 v28, v28, v57
	v_sub_f32_e32 v29, v29, v57
	v_sub_f32_e32 v30, v30, v57
	v_sub_f32_e32 v31, v31, v57
	v_mul_f32_e32 v28, 0x3fb8aa3b, v28
	v_mul_f32_e32 v29, 0x3fb8aa3b, v29
	v_mul_f32_e32 v30, 0x3fb8aa3b, v30
	v_mul_f32_e32 v31, 0x3fb8aa3b, v31
	v_sub_f32_e32 v32, v32, v58
	v_sub_f32_e32 v33, v33, v58
	v_sub_f32_e32 v34, v34, v58
	v_sub_f32_e32 v35, v35, v58
	v_mul_f32_e32 v32, 0x3fb8aa3b, v32
	v_mul_f32_e32 v33, 0x3fb8aa3b, v33
	v_mul_f32_e32 v34, 0x3fb8aa3b, v34
	v_mul_f32_e32 v35, 0x3fb8aa3b, v35
	v_sub_f32_e32 v36, v36, v59
	v_sub_f32_e32 v37, v37, v59
	v_sub_f32_e32 v38, v38, v59
	v_sub_f32_e32 v39, v39, v59
	v_mul_f32_e32 v36, 0x3fb8aa3b, v36
	v_mul_f32_e32 v37, 0x3fb8aa3b, v37
	v_mul_f32_e32 v38, 0x3fb8aa3b, v38
	v_mul_f32_e32 v39, 0x3fb8aa3b, v39
	v_exp_f32_e32 v24, v24
	v_exp_f32_e32 v25, v25
	v_exp_f32_e32 v26, v26
	v_exp_f32_e32 v27, v27
	v_exp_f32_e32 v28, v28
	v_exp_f32_e32 v29, v29
	v_exp_f32_e32 v30, v30
	v_exp_f32_e32 v31, v31
	v_exp_f32_e32 v32, v32
	v_exp_f32_e32 v33, v33
	v_exp_f32_e32 v34, v34
	v_exp_f32_e32 v35, v35
	v_exp_f32_e32 v36, v36
	v_exp_f32_e32 v37, v37
	v_exp_f32_e32 v38, v38
	v_exp_f32_e32 v39, v39
	v_add_f32_e32 v56, v24, v25
	v_add_f32_e32 v56, v26, v56
	v_add_f32_e32 v56, v27, v56
	v_add_f32_e32 v57, v28, v29
	v_add_f32_e32 v57, v30, v57
	v_add_f32_e32 v57, v31, v57
	v_add_f32_e32 v58, v32, v33
	v_add_f32_e32 v58, v34, v58
	v_add_f32_e32 v58, v35, v58
	v_add_f32_e32 v59, v36, v37
	v_add_f32_e32 v59, v38, v59
	v_add_f32_e32 v59, v39, v59
	ds_bpermute_b32 v60, v8, v56
	ds_bpermute_b32 v61, v8, v57
	ds_bpermute_b32 v62, v8, v58
	ds_bpermute_b32 v63, v8, v59
	s_waitcnt lgkmcnt(3)
	v_add_f32_e32 v56, v56, v60
	s_waitcnt lgkmcnt(2)
	v_add_f32_e32 v57, v57, v61
	s_waitcnt lgkmcnt(1)
	v_add_f32_e32 v58, v58, v62
	s_waitcnt lgkmcnt(0)
	v_add_f32_e32 v59, v59, v63
	ds_bpermute_b32 v60, v9, v56
	ds_bpermute_b32 v61, v9, v57
	ds_bpermute_b32 v62, v9, v58
	ds_bpermute_b32 v63, v9, v59
	s_waitcnt lgkmcnt(3)
	v_add_f32_e32 v56, v56, v60
	s_waitcnt lgkmcnt(2)
	v_add_f32_e32 v57, v57, v61
	s_waitcnt lgkmcnt(1)
	v_add_f32_e32 v58, v58, v62
	s_waitcnt lgkmcnt(0)
	v_add_f32_e32 v59, v59, v63
	ds_bpermute_b32 v60, v10, v56
	ds_bpermute_b32 v61, v10, v57
	ds_bpermute_b32 v62, v10, v58
	ds_bpermute_b32 v63, v10, v59
	s_waitcnt lgkmcnt(3)
	v_add_f32_e32 v56, v56, v60
	s_waitcnt lgkmcnt(2)
	v_add_f32_e32 v57, v57, v61
	s_waitcnt lgkmcnt(1)
	v_add_f32_e32 v58, v58, v62
	s_waitcnt lgkmcnt(0)
	v_add_f32_e32 v59, v59, v63
	ds_bpermute_b32 v60, v11, v56
	ds_bpermute_b32 v61, v11, v57
	ds_bpermute_b32 v62, v11, v58
	ds_bpermute_b32 v63, v11, v59
	s_waitcnt lgkmcnt(3)
	v_add_f32_e32 v56, v56, v60
	s_waitcnt lgkmcnt(2)
	v_add_f32_e32 v57, v57, v61
	s_waitcnt lgkmcnt(1)
	v_add_f32_e32 v58, v58, v62
	s_waitcnt lgkmcnt(0)
	v_add_f32_e32 v59, v59, v63
	ds_bpermute_b32 v60, v12, v56
	ds_bpermute_b32 v61, v12, v57
	ds_bpermute_b32 v62, v12, v58
	ds_bpermute_b32 v63, v12, v59
	s_waitcnt lgkmcnt(3)
	v_add_f32_e32 v56, v56, v60
	s_waitcnt lgkmcnt(2)
	v_add_f32_e32 v57, v57, v61
	s_waitcnt lgkmcnt(1)
	v_add_f32_e32 v58, v58, v62
	s_waitcnt lgkmcnt(0)
	v_add_f32_e32 v59, v59, v63
	ds_bpermute_b32 v60, v13, v56
	ds_bpermute_b32 v61, v13, v57
	ds_bpermute_b32 v62, v13, v58
	ds_bpermute_b32 v63, v13, v59
	s_waitcnt lgkmcnt(3)
	v_add_f32_e32 v56, v56, v60
	s_waitcnt lgkmcnt(2)
	v_add_f32_e32 v57, v57, v61
	s_waitcnt lgkmcnt(1)
	v_add_f32_e32 v58, v58, v62
	s_waitcnt lgkmcnt(0)
; DEV void store_bf4(bf16_t* p, f32x4 v) { uint2 w; w.x = cvt_pk_bf16(v[0], v[1]); w.y = cvt_pk_bf16(v[2], v[3]); *(uint2*)p = w; }
; DEV float wave_sum(float v) {
; #pragma unroll
;     for (int o = 32; o >= 1; o >>= 1) v += __shfl_xor(v, o);
;     return v;
; }
; DEV float wave_max(float v) {
; #pragma unroll
;     for (int o = 32; o >= 1; o >>= 1) v = fmaxf(v, __shfl_xor(v, o));
;     return v;
; }
; __global__ void __launch_bounds__(512) hymba_fwd(Params p) {
;     ...
;     for (int r = bid * 8 + wid; r < TP * 4; r += G * 8) {
;         const f32x4 v = __builtin_nontemporal_load((const f32x4*)(sc + (size_t)r * 256 + lane * 4));
;         const float mx = wave_max(fmaxf(fmaxf(v[0], v[1]), fmaxf(v[2], v[3])));
;         f32x4 e; e[0] = __expf(v[0] - mx); e[1] = __expf(v[1] - mx); e[2] = __expf(v[2] - mx); e[3] = __expf(v[3] - mx);
;         const float inv = 1.f / wave_sum(e[0] + e[1] + e[2] + e[3]);
;         store_bf4(pb + (size_t)(r >> 2) * LDP + (r & 3) * 256 + lane * 4, e * inv);
	v_add_f32_e32 v59, v59, v63
	v_div_scale_f32 v64, s[16:17], v56, v56, 1.0
	v_rcp_f32_e32 v65, v64
	v_div_scale_f32 v66, vcc, 1.0, v56, 1.0
	v_fma_f32 v67, -v64, v65, 1.0
	v_fmac_f32_e32 v65, v67, v65
	v_mul_f32_e32 v67, v66, v65
	v_fma_f32 v68, -v64, v67, v66
	v_fmac_f32_e32 v67, v68, v65
	v_fma_f32 v64, -v64, v67, v66
	v_div_fmas_f32 v64, v64, v65, v67
	v_div_fixup_f32 v56, v64, v56, 1.0
	v_mul_f32_e32 v24, v24, v56
	v_mul_f32_e32 v25, v25, v56
	v_mul_f32_e32 v26, v26, v56
	v_mul_f32_e32 v27, v27, v56
	v_cvt_pk_bf16_f32 v24, v24, v25
	v_cvt_pk_bf16_f32 v25, v26, v27
	global_store_dwordx2 v[20:21], v[24:25], off
	v_lshl_add_u64 v[20:21], v[20:21], 0, s[10:11]
	v_div_scale_f32 v64, s[16:17], v57, v57, 1.0
	v_rcp_f32_e32 v65, v64
	v_div_scale_f32 v66, vcc, 1.0, v57, 1.0
	v_fma_f32 v67, -v64, v65, 1.0
	v_fmac_f32_e32 v65, v67, v65
	v_mul_f32_e32 v67, v66, v65
	v_fma_f32 v68, -v64, v67, v66
	v_fmac_f32_e32 v67, v68, v65
	v_fma_f32 v64, -v64, v67, v66
	v_div_fmas_f32 v64, v64, v65, v67
	v_div_fixup_f32 v57, v64, v57, 1.0
	v_mul_f32_e32 v28, v28, v57
	v_mul_f32_e32 v29, v29, v57
	v_mul_f32_e32 v30, v30, v57
	v_mul_f32_e32 v31, v31, v57
	v_cvt_pk_bf16_f32 v28, v28, v29
	v_cvt_pk_bf16_f32 v29, v30, v31
	global_store_dwordx2 v[20:21], v[28:29], off
	v_lshl_add_u64 v[20:21], v[20:21], 0, s[10:11]
	v_div_scale_f32 v64, s[16:17], v58, v58, 1.0
	v_rcp_f32_e32 v65, v64
	v_div_scale_f32 v66, vcc, 1.0, v58, 1.0
	v_fma_f32 v67, -v64, v65, 1.0
	v_fmac_f32_e32 v65, v67, v65
	v_mul_f32_e32 v67, v66, v65
	v_fma_f32 v68, -v64, v67, v66
	v_fmac_f32_e32 v67, v68, v65
	v_fma_f32 v64, -v64, v67, v66
	v_div_fmas_f32 v64, v64, v65, v67
	v_div_fixup_f32 v58, v64, v58, 1.0
	v_mul_f32_e32 v32, v32, v58
	v_mul_f32_e32 v33, v33, v58
	v_mul_f32_e32 v34, v34, v58
	v_mul_f32_e32 v35, v35, v58
	v_cvt_pk_bf16_f32 v32, v32, v33
	v_cvt_pk_bf16_f32 v33, v34, v35
	global_store_dwordx2 v[20:21], v[32:33], off
	v_lshl_add_u64 v[20:21], v[20:21], 0, s[10:11]
	v_div_scale_f32 v64, s[16:17], v59, v59, 1.0
	v_rcp_f32_e32 v65, v64
	v_div_scale_f32 v66, vcc, 1.0, v59, 1.0
	v_fma_f32 v67, -v64, v65, 1.0
	v_fmac_f32_e32 v65, v67, v65
	v_mul_f32_e32 v67, v66, v65
	v_fma_f32 v68, -v64, v67, v66
	v_fmac_f32_e32 v67, v68, v65
	v_fma_f32 v64, -v64, v67, v66
	v_div_fmas_f32 v64, v64, v65, v67
	v_div_fixup_f32 v59, v64, v59, 1.0
	v_mul_f32_e32 v36, v36, v59
	v_mul_f32_e32 v37, v37, v59
	v_mul_f32_e32 v38, v38, v59
	v_mul_f32_e32 v39, v39, v59
	v_cvt_pk_bf16_f32 v36, v36, v37
	v_cvt_pk_bf16_f32 v37, v38, v39
	global_store_dwordx2 v[20:21], v[36:37], off
	v_lshl_add_u64 v[20:21], v[20:21], 0, s[10:11]
	global_load_dwordx4 v[24:27], v[4:5], off nt
	v_lshl_add_u64 v[4:5], v[4:5], 0, s[8:9]
	global_load_dwordx4 v[28:31], v[4:5], off nt
	v_lshl_add_u64 v[4:5], v[4:5], 0, s[8:9]
	global_load_dwordx4 v[32:35], v[4:5], off nt
	v_lshl_add_u64 v[4:5], v[4:5], 0, s[8:9]
	global_load_dwordx4 v[36:39], v[4:5], off nt
	v_lshl_add_u64 v[4:5], v[4:5], 0, s[8:9]
	s_waitcnt vmcnt(8)
	v_max_f32_e32 v56, v43, v43
	v_max_f32_e32 v60, v42, v42
	v_max_f32_e32 v56, v60, v56
	v_max3_f32 v56, v40, v41, v56
	v_max_f32_e32 v57, v47, v47
	v_max_f32_e32 v61, v46, v46
	v_max_f32_e32 v57, v61, v57
	v_max3_f32 v57, v44, v45, v57
	v_max_f32_e32 v58, v51, v51
	v_max_f32_e32 v62, v50, v50
	v_max_f32_e32 v58, v62, v58
	v_max3_f32 v58, v48, v49, v58
	v_max_f32_e32 v59, v55, v55
	v_max_f32_e32 v63, v54, v54
	v_max_f32_e32 v59, v63, v59
	v_max3_f32 v59, v52, v53, v59
	ds_bpermute_b32 v60, v8, v56
	ds_bpermute_b32 v61, v8, v57
	ds_bpermute_b32 v62, v8, v58
	ds_bpermute_b32 v63, v8, v59
	s_waitcnt lgkmcnt(3)
	v_max_f32_e32 v60, v60, v60
	v_max_f32_e32 v56, v56, v60
	s_waitcnt lgkmcnt(2)
	v_max_f32_e32 v61, v61, v61
	v_max_f32_e32 v57, v57, v61
	s_waitcnt lgkmcnt(1)
	v_max_f32_e32 v62, v62, v62
	v_max_f32_e32 v58, v58, v62
	s_waitcnt lgkmcnt(0)
	v_max_f32_e32 v63, v63, v63
	v_max_f32_e32 v59, v59, v63
	ds_bpermute_b32 v60, v9, v56
	ds_bpermute_b32 v61, v9, v57
	ds_bpermute_b32 v62, v9, v58
	ds_bpermute_b32 v63, v9, v59
	s_waitcnt lgkmcnt(3)
	v_max_f32_e32 v60, v60, v60
	v_max_f32_e32 v56, v56, v60
	s_waitcnt lgkmcnt(2)
	v_max_f32_e32 v61, v61, v61
	v_max_f32_e32 v57, v57, v61
	s_waitcnt lgkmcnt(1)
	v_max_f32_e32 v62, v62, v62
	v_max_f32_e32 v58, v58, v62
	s_waitcnt lgkmcnt(0)
	v_max_f32_e32 v63, v63, v63
	v_max_f32_e32 v59, v59, v63
	ds_bpermute_b32 v60, v10, v56
	ds_bpermute_b32 v61, v10, v57
	ds_bpermute_b32 v62, v10, v58
	ds_bpermute_b32 v63, v10, v59
	s_waitcnt lgkmcnt(3)
	v_max_f32_e32 v60, v60, v60
	v_max_f32_e32 v56, v56, v60
	s_waitcnt lgkmcnt(2)
	v_max_f32_e32 v61, v61, v61
	v_max_f32_e32 v57, v57, v61
	s_waitcnt lgkmcnt(1)
	v_max_f32_e32 v62, v62, v62
	v_max_f32_e32 v58, v58, v62
	s_waitcnt lgkmcnt(0)
	v_max_f32_e32 v63, v63, v63
	v_max_f32_e32 v59, v59, v63
	ds_bpermute_b32 v60, v11, v56
	ds_bpermute_b32 v61, v11, v57
	ds_bpermute_b32 v62, v11, v58
	ds_bpermute_b32 v63, v11, v59
	s_waitcnt lgkmcnt(3)
	v_max_f32_e32 v60, v60, v60
	v_max_f32_e32 v56, v56, v60
	s_waitcnt lgkmcnt(2)
	v_max_f32_e32 v61, v61, v61
	v_max_f32_e32 v57, v57, v61
	s_waitcnt lgkmcnt(1)
	v_max_f32_e32 v62, v62, v62
	v_max_f32_e32 v58, v58, v62
	s_waitcnt lgkmcnt(0)
	v_max_f32_e32 v63, v63, v63
	v_max_f32_e32 v59, v59, v63
	ds_bpermute_b32 v60, v12, v56
	ds_bpermute_b32 v61, v12, v57
	ds_bpermute_b32 v62, v12, v58
	ds_bpermute_b32 v63, v12, v59
	s_waitcnt lgkmcnt(3)
	v_max_f32_e32 v60, v60, v60
	v_max_f32_e32 v56, v56, v60
	s_waitcnt lgkmcnt(2)
	v_max_f32_e32 v61, v61, v61
	v_max_f32_e32 v57, v57, v61
	s_waitcnt lgkmcnt(1)
	v_max_f32_e32 v62, v62, v62
	v_max_f32_e32 v58, v58, v62
	s_waitcnt lgkmcnt(0)
; DEV void store_bf4(bf16_t* p, f32x4 v) { uint2 w; w.x = cvt_pk_bf16(v[0], v[1]); w.y = cvt_pk_bf16(v[2], v[3]); *(uint2*)p = w; }
; DEV float wave_sum(float v) {
; #pragma unroll
;     for (int o = 32; o >= 1; o >>= 1) v += __shfl_xor(v, o);
;     return v;
; }
; DEV float wave_max(float v) {
; #pragma unroll
;     for (int o = 32; o >= 1; o >>= 1) v = fmaxf(v, __shfl_xor(v, o));
;     return v;
; }
; __global__ void __launch_bounds__(512) hymba_fwd(Params p) {
;     ...
;     for (int r = bid * 8 + wid; r < TP * 4; r += G * 8) {
;         const f32x4 v = __builtin_nontemporal_load((const f32x4*)(sc + (size_t)r * 256 + lane * 4));
;         const float mx = wave_max(fmaxf(fmaxf(v[0], v[1]), fmaxf(v[2], v[3])));
;         f32x4 e; e[0] = __expf(v[0] - mx); e[1] = __expf(v[1] - mx); e[2] = __expf(v[2] - mx); e[3] = __expf(v[3] - mx);
;         const float inv = 1.f / wave_sum(e[0] + e[1] + e[2] + e[3]);
;         store_bf4(pb + (size_t)(r >> 2) * LDP + (r & 3) * 256 + lane * 4, e * inv);
	v_max_f32_e32 v63, v63, v63
	v_max_f32_e32 v59, v59, v63
	ds_bpermute_b32 v60, v13, v56
	ds_bpermute_b32 v61, v13, v57
	ds_bpermute_b32 v62, v13, v58
	ds_bpermute_b32 v63, v13, v59
	s_waitcnt lgkmcnt(3)
	v_max_f32_e32 v60, v60, v60
	v_max_f32_e32 v56, v56, v60
	s_waitcnt lgkmcnt(2)
	v_max_f32_e32 v61, v61, v61
	v_max_f32_e32 v57, v57, v61
	s_waitcnt lgkmcnt(1)
	v_max_f32_e32 v62, v62, v62
	v_max_f32_e32 v58, v58, v62
	s_waitcnt lgkmcnt(0)
	v_max_f32_e32 v63, v63, v63
	v_max_f32_e32 v59, v59, v63
	v_sub_f32_e32 v40, v40, v56
	v_sub_f32_e32 v41, v41, v56
	v_sub_f32_e32 v42, v42, v56
	v_sub_f32_e32 v43, v43, v56
	v_mul_f32_e32 v40, 0x3fb8aa3b, v40
	v_mul_f32_e32 v41, 0x3fb8aa3b, v41
	v_mul_f32_e32 v42, 0x3fb8aa3b, v42
	v_mul_f32_e32 v43, 0x3fb8aa3b, v43
	v_sub_f32_e32 v44, v44, v57
	v_sub_f32_e32 v45, v45, v57
	v_sub_f32_e32 v46, v46, v57
	v_sub_f32_e32 v47, v47, v57
	v_mul_f32_e32 v44, 0x3fb8aa3b, v44
	v_mul_f32_e32 v45, 0x3fb8aa3b, v45
	v_mul_f32_e32 v46, 0x3fb8aa3b, v46
	v_mul_f32_e32 v47, 0x3fb8aa3b, v47
	v_sub_f32_e32 v48, v48, v58
	v_sub_f32_e32 v49, v49, v58
	v_sub_f32_e32 v50, v50, v58
	v_sub_f32_e32 v51, v51, v58
	v_mul_f32_e32 v48, 0x3fb8aa3b, v48
	v_mul_f32_e32 v49, 0x3fb8aa3b, v49
	v_mul_f32_e32 v50, 0x3fb8aa3b, v50
	v_mul_f32_e32 v51, 0x3fb8aa3b, v51
	v_sub_f32_e32 v52, v52, v59
	v_sub_f32_e32 v53, v53, v59
	v_sub_f32_e32 v54, v54, v59
	v_sub_f32_e32 v55, v55, v59
	v_mul_f32_e32 v52, 0x3fb8aa3b, v52
	v_mul_f32_e32 v53, 0x3fb8aa3b, v53
	v_mul_f32_e32 v54, 0x3fb8aa3b, v54
	v_mul_f32_e32 v55, 0x3fb8aa3b, v55
	v_exp_f32_e32 v40, v40
	v_exp_f32_e32 v41, v41
	v_exp_f32_e32 v42, v42
	v_exp_f32_e32 v43, v43
	v_exp_f32_e32 v44, v44
	v_exp_f32_e32 v45, v45
	v_exp_f32_e32 v46, v46
	v_exp_f32_e32 v47, v47
	v_exp_f32_e32 v48, v48
	v_exp_f32_e32 v49, v49
	v_exp_f32_e32 v50, v50
	v_exp_f32_e32 v51, v51
	v_exp_f32_e32 v52, v52
	v_exp_f32_e32 v53, v53
	v_exp_f32_e32 v54, v54
	v_exp_f32_e32 v55, v55
	v_add_f32_e32 v56, v40, v41
	v_add_f32_e32 v56, v42, v56
	v_add_f32_e32 v56, v43, v56
	v_add_f32_e32 v57, v44, v45
	v_add_f32_e32 v57, v46, v57
	v_add_f32_e32 v57, v47, v57
	v_add_f32_e32 v58, v48, v49
	v_add_f32_e32 v58, v50, v58
	v_add_f32_e32 v58, v51, v58
	v_add_f32_e32 v59, v52, v53
	v_add_f32_e32 v59, v54, v59
	v_add_f32_e32 v59, v55, v59
	ds_bpermute_b32 v60, v8, v56
	ds_bpermute_b32 v61, v8, v57
	ds_bpermute_b32 v62, v8, v58
	ds_bpermute_b32 v63, v8, v59
	s_waitcnt lgkmcnt(3)
	v_add_f32_e32 v56, v56, v60
	s_waitcnt lgkmcnt(2)
	v_add_f32_e32 v57, v57, v61
	s_waitcnt lgkmcnt(1)
	v_add_f32_e32 v58, v58, v62
	s_waitcnt lgkmcnt(0)
	v_add_f32_e32 v59, v59, v63
	ds_bpermute_b32 v60, v9, v56
	ds_bpermute_b32 v61, v9, v57
	ds_bpermute_b32 v62, v9, v58
	ds_bpermute_b32 v63, v9, v59
	s_waitcnt lgkmcnt(3)
	v_add_f32_e32 v56, v56, v60
	s_waitcnt lgkmcnt(2)
	v_add_f32_e32 v57, v57, v61
	s_waitcnt lgkmcnt(1)
	v_add_f32_e32 v58, v58, v62
	s_waitcnt lgkmcnt(0)
	v_add_f32_e32 v59, v59, v63
	ds_bpermute_b32 v60, v10, v56
	ds_bpermute_b32 v61, v10, v57
	ds_bpermute_b32 v62, v10, v58
	ds_bpermute_b32 v63, v10, v59
	s_waitcnt lgkmcnt(3)
	v_add_f32_e32 v56, v56, v60
	s_waitcnt lgkmcnt(2)
	v_add_f32_e32 v57, v57, v61
	s_waitcnt lgkmcnt(1)
	v_add_f32_e32 v58, v58, v62
	s_waitcnt lgkmcnt(0)
	v_add_f32_e32 v59, v59, v63
	ds_bpermute_b32 v60, v11, v56
	ds_bpermute_b32 v61, v11, v57
	ds_bpermute_b32 v62, v11, v58
	ds_bpermute_b32 v63, v11, v59
	s_waitcnt lgkmcnt(3)
	v_add_f32_e32 v56, v56, v60
	s_waitcnt lgkmcnt(2)
	v_add_f32_e32 v57, v57, v61
	s_waitcnt lgkmcnt(1)
	v_add_f32_e32 v58, v58, v62
	s_waitcnt lgkmcnt(0)
	v_add_f32_e32 v59, v59, v63
	ds_bpermute_b32 v60, v12, v56
	ds_bpermute_b32 v61, v12, v57
	ds_bpermute_b32 v62, v12, v58
	ds_bpermute_b32 v63, v12, v59
	s_waitcnt lgkmcnt(3)
	v_add_f32_e32 v56, v56, v60
	s_waitcnt lgkmcnt(2)
	v_add_f32_e32 v57, v57, v61
	s_waitcnt lgkmcnt(1)
	v_add_f32_e32 v58, v58, v62
	s_waitcnt lgkmcnt(0)
	v_add_f32_e32 v59, v59, v63
	ds_bpermute_b32 v60, v13, v56
	ds_bpermute_b32 v61, v13, v57
	ds_bpermute_b32 v62, v13, v58
	ds_bpermute_b32 v63, v13, v59
	s_waitcnt lgkmcnt(3)
	v_add_f32_e32 v56, v56, v60
	s_waitcnt lgkmcnt(2)
	v_add_f32_e32 v57, v57, v61
	s_waitcnt lgkmcnt(1)
	v_add_f32_e32 v58, v58, v62
	s_waitcnt lgkmcnt(0)
	v_add_f32_e32 v59, v59, v63
	v_div_scale_f32 v64, s[16:17], v56, v56, 1.0
	v_rcp_f32_e32 v65, v64
	v_div_scale_f32 v66, vcc, 1.0, v56, 1.0
	v_fma_f32 v67, -v64, v65, 1.0
	v_fmac_f32_e32 v65, v67, v65
	v_mul_f32_e32 v67, v66, v65
	v_fma_f32 v68, -v64, v67, v66
	v_fmac_f32_e32 v67, v68, v65
	v_fma_f32 v64, -v64, v67, v66
	v_div_fmas_f32 v64, v64, v65, v67
	v_div_fixup_f32 v56, v64, v56, 1.0
	v_mul_f32_e32 v40, v40, v56
	v_mul_f32_e32 v41, v41, v56
	v_mul_f32_e32 v42, v42, v56
	v_mul_f32_e32 v43, v43, v56
	v_cvt_pk_bf16_f32 v40, v40, v41
	v_cvt_pk_bf16_f32 v41, v42, v43
	global_store_dwordx2 v[20:21], v[40:41], off
	v_lshl_add_u64 v[20:21], v[20:21], 0, s[10:11]
	v_div_scale_f32 v64, s[16:17], v57, v57, 1.0
	v_rcp_f32_e32 v65, v64
	v_div_scale_f32 v66, vcc, 1.0, v57, 1.0
	v_fma_f32 v67, -v64, v65, 1.0
	v_fmac_f32_e32 v65, v67, v65
	v_mul_f32_e32 v67, v66, v65
	v_fma_f32 v68, -v64, v67, v66
	v_fmac_f32_e32 v67, v68, v65
	v_fma_f32 v64, -v64, v67, v66
	v_div_fmas_f32 v64, v64, v65, v67
	v_div_fixup_f32 v57, v64, v57, 1.0
	v_mul_f32_e32 v44, v44, v57
	v_mul_f32_e32 v45, v45, v57
	v_mul_f32_e32 v46, v46, v57
	v_mul_f32_e32 v47, v47, v57
	v_cvt_pk_bf16_f32 v44, v44, v45
	v_cvt_pk_bf16_f32 v45, v46, v47
	global_store_dwordx2 v[20:21], v[44:45], off
	v_lshl_add_u64 v[20:21], v[20:21], 0, s[10:11]
	v_div_scale_f32 v64, s[16:17], v58, v58, 1.0
	v_rcp_f32_e32 v65, v64
	v_div_scale_f32 v66, vcc, 1.0, v58, 1.0
; DEV void store_bf4(bf16_t* p, f32x4 v) { uint2 w; w.x = cvt_pk_bf16(v[0], v[1]); w.y = cvt_pk_bf16(v[2], v[3]); *(uint2*)p = w; }
; DEV float wave_sum(float v) {
; #pragma unroll
;     for (int o = 32; o >= 1; o >>= 1) v += __shfl_xor(v, o);
;     return v;
; }
; DEV float wave_max(float v) {
; #pragma unroll
;     for (int o = 32; o >= 1; o >>= 1) v = fmaxf(v, __shfl_xor(v, o));
;     return v;
; }
; __global__ void __launch_bounds__(512) hymba_fwd(Params p) {
;     ...
;     for (int r = bid * 8 + wid; r < TP * 4; r += G * 8) {
;         const f32x4 v = __builtin_nontemporal_load((const f32x4*)(sc + (size_t)r * 256 + lane * 4));
;         const float mx = wave_max(fmaxf(fmaxf(v[0], v[1]), fmaxf(v[2], v[3])));
;         f32x4 e; e[0] = __expf(v[0] - mx); e[1] = __expf(v[1] - mx); e[2] = __expf(v[2] - mx); e[3] = __expf(v[3] - mx);
;         const float inv = 1.f / wave_sum(e[0] + e[1] + e[2] + e[3]);
;         store_bf4(pb + (size_t)(r >> 2) * LDP + (r & 3) * 256 + lane * 4, e * inv);
	v_fma_f32 v67, -v64, v65, 1.0
	v_fmac_f32_e32 v65, v67, v65
	v_mul_f32_e32 v67, v66, v65
	v_fma_f32 v68, -v64, v67, v66
	v_fmac_f32_e32 v67, v68, v65
	v_fma_f32 v64, -v64, v67, v66
	v_div_fmas_f32 v64, v64, v65, v67
	v_div_fixup_f32 v58, v64, v58, 1.0
	v_mul_f32_e32 v48, v48, v58
	v_mul_f32_e32 v49, v49, v58
	v_mul_f32_e32 v50, v50, v58
	v_mul_f32_e32 v51, v51, v58
	v_cvt_pk_bf16_f32 v48, v48, v49
	v_cvt_pk_bf16_f32 v49, v50, v51
	global_store_dwordx2 v[20:21], v[48:49], off
	v_lshl_add_u64 v[20:21], v[20:21], 0, s[10:11]
	v_div_scale_f32 v64, s[16:17], v59, v59, 1.0
	v_rcp_f32_e32 v65, v64
	v_div_scale_f32 v66, vcc, 1.0, v59, 1.0
	v_fma_f32 v67, -v64, v65, 1.0
	v_fmac_f32_e32 v65, v67, v65
	v_mul_f32_e32 v67, v66, v65
	v_fma_f32 v68, -v64, v67, v66
	v_fmac_f32_e32 v67, v68, v65
	v_fma_f32 v64, -v64, v67, v66
	v_div_fmas_f32 v64, v64, v65, v67
	v_div_fixup_f32 v59, v64, v59, 1.0
	v_mul_f32_e32 v52, v52, v59
	v_mul_f32_e32 v53, v53, v59
	v_mul_f32_e32 v54, v54, v59
	v_mul_f32_e32 v55, v55, v59
	v_cvt_pk_bf16_f32 v52, v52, v53
	v_cvt_pk_bf16_f32 v53, v54, v55
	global_store_dwordx2 v[20:21], v[52:53], off
	v_lshl_add_u64 v[20:21], v[20:21], 0, s[10:11]
	global_load_dwordx4 v[40:43], v[4:5], off nt
	v_lshl_add_u64 v[4:5], v[4:5], 0, s[8:9]
	global_load_dwordx4 v[44:47], v[4:5], off nt
	v_lshl_add_u64 v[4:5], v[4:5], 0, s[8:9]
	global_load_dwordx4 v[48:51], v[4:5], off nt
	v_lshl_add_u64 v[4:5], v[4:5], 0, s[8:9]
	global_load_dwordx4 v[52:55], v[4:5], off nt
	v_lshl_add_u64 v[4:5], v[4:5], 0, s[8:9]
	s_waitcnt vmcnt(8)
	v_max_f32_e32 v56, v27, v27
	v_max_f32_e32 v60, v26, v26
	v_max_f32_e32 v56, v60, v56
	v_max3_f32 v56, v24, v25, v56
	v_max_f32_e32 v57, v31, v31
	v_max_f32_e32 v61, v30, v30
	v_max_f32_e32 v57, v61, v57
	v_max3_f32 v57, v28, v29, v57
	v_max_f32_e32 v58, v35, v35
	v_max_f32_e32 v62, v34, v34
	v_max_f32_e32 v58, v62, v58
	v_max3_f32 v58, v32, v33, v58
	v_max_f32_e32 v59, v39, v39
	v_max_f32_e32 v63, v38, v38
	v_max_f32_e32 v59, v63, v59
	v_max3_f32 v59, v36, v37, v59
	ds_bpermute_b32 v60, v8, v56
	ds_bpermute_b32 v61, v8, v57
	ds_bpermute_b32 v62, v8, v58
	ds_bpermute_b32 v63, v8, v59
	s_waitcnt lgkmcnt(3)
	v_max_f32_e32 v60, v60, v60
	v_max_f32_e32 v56, v56, v60
	s_waitcnt lgkmcnt(2)
	v_max_f32_e32 v61, v61, v61
	v_max_f32_e32 v57, v57, v61
	s_waitcnt lgkmcnt(1)
	v_max_f32_e32 v62, v62, v62
	v_max_f32_e32 v58, v58, v62
	s_waitcnt lgkmcnt(0)
	v_max_f32_e32 v63, v63, v63
	v_max_f32_e32 v59, v59, v63
	ds_bpermute_b32 v60, v9, v56
	ds_bpermute_b32 v61, v9, v57
	ds_bpermute_b32 v62, v9, v58
	ds_bpermute_b32 v63, v9, v59
	s_waitcnt lgkmcnt(3)
	v_max_f32_e32 v60, v60, v60
	v_max_f32_e32 v56, v56, v60
	s_waitcnt lgkmcnt(2)
	v_max_f32_e32 v61, v61, v61
	v_max_f32_e32 v57, v57, v61
	s_waitcnt lgkmcnt(1)
	v_max_f32_e32 v62, v62, v62
	v_max_f32_e32 v58, v58, v62
	s_waitcnt lgkmcnt(0)
	v_max_f32_e32 v63, v63, v63
	v_max_f32_e32 v59, v59, v63
	ds_bpermute_b32 v60, v10, v56
	ds_bpermute_b32 v61, v10, v57
	ds_bpermute_b32 v62, v10, v58
	ds_bpermute_b32 v63, v10, v59
	s_waitcnt lgkmcnt(3)
	v_max_f32_e32 v60, v60, v60
	v_max_f32_e32 v56, v56, v60
	s_waitcnt lgkmcnt(2)
	v_max_f32_e32 v61, v61, v61
	v_max_f32_e32 v57, v57, v61
	s_waitcnt lgkmcnt(1)
	v_max_f32_e32 v62, v62, v62
	v_max_f32_e32 v58, v58, v62
	s_waitcnt lgkmcnt(0)
	v_max_f32_e32 v63, v63, v63
	v_max_f32_e32 v59, v59, v63
	ds_bpermute_b32 v60, v11, v56
	ds_bpermute_b32 v61, v11, v57
	ds_bpermute_b32 v62, v11, v58
	ds_bpermute_b32 v63, v11, v59
	s_waitcnt lgkmcnt(3)
	v_max_f32_e32 v60, v60, v60
	v_max_f32_e32 v56, v56, v60
	s_waitcnt lgkmcnt(2)
	v_max_f32_e32 v61, v61, v61
	v_max_f32_e32 v57, v57, v61
	s_waitcnt lgkmcnt(1)
	v_max_f32_e32 v62, v62, v62
	v_max_f32_e32 v58, v58, v62
	s_waitcnt lgkmcnt(0)
	v_max_f32_e32 v63, v63, v63
	v_max_f32_e32 v59, v59, v63
	ds_bpermute_b32 v60, v12, v56
	ds_bpermute_b32 v61, v12, v57
	ds_bpermute_b32 v62, v12, v58
	ds_bpermute_b32 v63, v12, v59
	s_waitcnt lgkmcnt(3)
	v_max_f32_e32 v60, v60, v60
	v_max_f32_e32 v56, v56, v60
	s_waitcnt lgkmcnt(2)
	v_max_f32_e32 v61, v61, v61
	v_max_f32_e32 v57, v57, v61
	s_waitcnt lgkmcnt(1)
	v_max_f32_e32 v62, v62, v62
	v_max_f32_e32 v58, v58, v62
	s_waitcnt lgkmcnt(0)
	v_max_f32_e32 v63, v63, v63
	v_max_f32_e32 v59, v59, v63
	ds_bpermute_b32 v60, v13, v56
	ds_bpermute_b32 v61, v13, v57
	ds_bpermute_b32 v62, v13, v58
	ds_bpermute_b32 v63, v13, v59
	s_waitcnt lgkmcnt(3)
	v_max_f32_e32 v60, v60, v60
	v_max_f32_e32 v56, v56, v60
	s_waitcnt lgkmcnt(2)
	v_max_f32_e32 v61, v61, v61
	v_max_f32_e32 v57, v57, v61
	s_waitcnt lgkmcnt(1)
	v_max_f32_e32 v62, v62, v62
	v_max_f32_e32 v58, v58, v62
	s_waitcnt lgkmcnt(0)
	v_max_f32_e32 v63, v63, v63
	v_max_f32_e32 v59, v59, v63
	v_sub_f32_e32 v24, v24, v56
	v_sub_f32_e32 v25, v25, v56
	v_sub_f32_e32 v26, v26, v56
	v_sub_f32_e32 v27, v27, v56
	v_mul_f32_e32 v24, 0x3fb8aa3b, v24
	v_mul_f32_e32 v25, 0x3fb8aa3b, v25
	v_mul_f32_e32 v26, 0x3fb8aa3b, v26
	v_mul_f32_e32 v27, 0x3fb8aa3b, v27
	v_sub_f32_e32 v28, v28, v57
	v_sub_f32_e32 v29, v29, v57
	v_sub_f32_e32 v30, v30, v57
	v_sub_f32_e32 v31, v31, v57
	v_mul_f32_e32 v28, 0x3fb8aa3b, v28
	v_mul_f32_e32 v29, 0x3fb8aa3b, v29
	v_mul_f32_e32 v30, 0x3fb8aa3b, v30
	v_mul_f32_e32 v31, 0x3fb8aa3b, v31
	v_sub_f32_e32 v32, v32, v58
	v_sub_f32_e32 v33, v33, v58
	v_sub_f32_e32 v34, v34, v58
	v_sub_f32_e32 v35, v35, v58
	v_mul_f32_e32 v32, 0x3fb8aa3b, v32
	v_mul_f32_e32 v33, 0x3fb8aa3b, v33
	v_mul_f32_e32 v34, 0x3fb8aa3b, v34
	v_mul_f32_e32 v35, 0x3fb8aa3b, v35
	v_sub_f32_e32 v36, v36, v59
	v_sub_f32_e32 v37, v37, v59
	v_sub_f32_e32 v38, v38, v59
	v_sub_f32_e32 v39, v39, v59
	v_mul_f32_e32 v36, 0x3fb8aa3b, v36
	v_mul_f32_e32 v37, 0x3fb8aa3b, v37
	v_mul_f32_e32 v38, 0x3fb8aa3b, v38
	v_mul_f32_e32 v39, 0x3fb8aa3b, v39
	v_exp_f32_e32 v24, v24
	v_exp_f32_e32 v25, v25
	v_exp_f32_e32 v26, v26
	v_exp_f32_e32 v27, v27
	v_exp_f32_e32 v28, v28
	v_exp_f32_e32 v29, v29
	v_exp_f32_e32 v30, v30
	v_exp_f32_e32 v31, v31
	v_exp_f32_e32 v32, v32
	v_exp_f32_e32 v33, v33
	v_exp_f32_e32 v34, v34
	v_exp_f32_e32 v35, v35
	v_exp_f32_e32 v36, v36
	v_exp_f32_e32 v37, v37
	v_exp_f32_e32 v38, v38
	v_exp_f32_e32 v39, v39
	v_add_f32_e32 v56, v24, v25
	v_add_f32_e32 v56, v26, v56
	v_add_f32_e32 v56, v27, v56
	v_add_f32_e32 v57, v28, v29
	v_add_f32_e32 v57, v30, v57
	v_add_f32_e32 v57, v31, v57
	v_add_f32_e32 v58, v32, v33
	v_add_f32_e32 v58, v34, v58
	v_add_f32_e32 v58, v35, v58
	v_add_f32_e32 v59, v36, v37
	v_add_f32_e32 v59, v38, v59
	v_add_f32_e32 v59, v39, v59
	ds_bpermute_b32 v60, v8, v56
	ds_bpermute_b32 v61, v8, v57
	ds_bpermute_b32 v62, v8, v58
	ds_bpermute_b32 v63, v8, v59
	s_waitcnt lgkmcnt(3)
; DEV void store_bf4(bf16_t* p, f32x4 v) { uint2 w; w.x = cvt_pk_bf16(v[0], v[1]); w.y = cvt_pk_bf16(v[2], v[3]); *(uint2*)p = w; }
; DEV float wave_sum(float v) {
; #pragma unroll
;     for (int o = 32; o >= 1; o >>= 1) v += __shfl_xor(v, o);
;     return v;
; }
; DEV float wave_max(float v) {
; #pragma unroll
;     for (int o = 32; o >= 1; o >>= 1) v = fmaxf(v, __shfl_xor(v, o));
;     return v;
; }
; __global__ void __launch_bounds__(512) hymba_fwd(Params p) {
;     ...
;     for (int r = bid * 8 + wid; r < TP * 4; r += G * 8) {
;         const f32x4 v = __builtin_nontemporal_load((const f32x4*)(sc + (size_t)r * 256 + lane * 4));
;         const float mx = wave_max(fmaxf(fmaxf(v[0], v[1]), fmaxf(v[2], v[3])));
;         f32x4 e; e[0] = __expf(v[0] - mx); e[1] = __expf(v[1] - mx); e[2] = __expf(v[2] - mx); e[3] = __expf(v[3] - mx);
;         const float inv = 1.f / wave_sum(e[0] + e[1] + e[2] + e[3]);
;         store_bf4(pb + (size_t)(r >> 2) * LDP + (r & 3) * 256 + lane * 4, e * inv);
	v_add_f32_e32 v56, v56, v60
	s_waitcnt lgkmcnt(2)
	v_add_f32_e32 v57, v57, v61
	s_waitcnt lgkmcnt(1)
	v_add_f32_e32 v58, v58, v62
	s_waitcnt lgkmcnt(0)
	v_add_f32_e32 v59, v59, v63
	ds_bpermute_b32 v60, v9, v56
	ds_bpermute_b32 v61, v9, v57
	ds_bpermute_b32 v62, v9, v58
	ds_bpermute_b32 v63, v9, v59
	s_waitcnt lgkmcnt(3)
	v_add_f32_e32 v56, v56, v60
	s_waitcnt lgkmcnt(2)
	v_add_f32_e32 v57, v57, v61
	s_waitcnt lgkmcnt(1)
	v_add_f32_e32 v58, v58, v62
	s_waitcnt lgkmcnt(0)
	v_add_f32_e32 v59, v59, v63
	ds_bpermute_b32 v60, v10, v56
	ds_bpermute_b32 v61, v10, v57
	ds_bpermute_b32 v62, v10, v58
	ds_bpermute_b32 v63, v10, v59
	s_waitcnt lgkmcnt(3)
	v_add_f32_e32 v56, v56, v60
	s_waitcnt lgkmcnt(2)
	v_add_f32_e32 v57, v57, v61
	s_waitcnt lgkmcnt(1)
	v_add_f32_e32 v58, v58, v62
	s_waitcnt lgkmcnt(0)
	v_add_f32_e32 v59, v59, v63
	ds_bpermute_b32 v60, v11, v56
	ds_bpermute_b32 v61, v11, v57
	ds_bpermute_b32 v62, v11, v58
	ds_bpermute_b32 v63, v11, v59
	s_waitcnt lgkmcnt(3)
	v_add_f32_e32 v56, v56, v60
	s_waitcnt lgkmcnt(2)
	v_add_f32_e32 v57, v57, v61
	s_waitcnt lgkmcnt(1)
	v_add_f32_e32 v58, v58, v62
	s_waitcnt lgkmcnt(0)
	v_add_f32_e32 v59, v59, v63
	ds_bpermute_b32 v60, v12, v56
	ds_bpermute_b32 v61, v12, v57
	ds_bpermute_b32 v62, v12, v58
	ds_bpermute_b32 v63, v12, v59
	s_waitcnt lgkmcnt(3)
	v_add_f32_e32 v56, v56, v60
	s_waitcnt lgkmcnt(2)
	v_add_f32_e32 v57, v57, v61
	s_waitcnt lgkmcnt(1)
	v_add_f32_e32 v58, v58, v62
	s_waitcnt lgkmcnt(0)
	v_add_f32_e32 v59, v59, v63
	ds_bpermute_b32 v60, v13, v56
	ds_bpermute_b32 v61, v13, v57
	ds_bpermute_b32 v62, v13, v58
	ds_bpermute_b32 v63, v13, v59
	s_waitcnt lgkmcnt(3)
	v_add_f32_e32 v56, v56, v60
	s_waitcnt lgkmcnt(2)
	v_add_f32_e32 v57, v57, v61
	s_waitcnt lgkmcnt(1)
	v_add_f32_e32 v58, v58, v62
	s_waitcnt lgkmcnt(0)
	v_add_f32_e32 v59, v59, v63
	v_div_scale_f32 v64, s[16:17], v56, v56, 1.0
	v_rcp_f32_e32 v65, v64
	v_div_scale_f32 v66, vcc, 1.0, v56, 1.0
	v_fma_f32 v67, -v64, v65, 1.0
	v_fmac_f32_e32 v65, v67, v65
	v_mul_f32_e32 v67, v66, v65
	v_fma_f32 v68, -v64, v67, v66
	v_fmac_f32_e32 v67, v68, v65
	v_fma_f32 v64, -v64, v67, v66
	v_div_fmas_f32 v64, v64, v65, v67
	v_div_fixup_f32 v56, v64, v56, 1.0
	v_mul_f32_e32 v24, v24, v56
	v_mul_f32_e32 v25, v25, v56
	v_mul_f32_e32 v26, v26, v56
	v_mul_f32_e32 v27, v27, v56
	v_cvt_pk_bf16_f32 v24, v24, v25
	v_cvt_pk_bf16_f32 v25, v26, v27
	global_store_dwordx2 v[20:21], v[24:25], off
	v_lshl_add_u64 v[20:21], v[20:21], 0, s[10:11]
	v_div_scale_f32 v64, s[16:17], v57, v57, 1.0
	v_rcp_f32_e32 v65, v64
	v_div_scale_f32 v66, vcc, 1.0, v57, 1.0
	v_fma_f32 v67, -v64, v65, 1.0
	v_fmac_f32_e32 v65, v67, v65
	v_mul_f32_e32 v67, v66, v65
	v_fma_f32 v68, -v64, v67, v66
	v_fmac_f32_e32 v67, v68, v65
	v_fma_f32 v64, -v64, v67, v66
	v_div_fmas_f32 v64, v64, v65, v67
	v_div_fixup_f32 v57, v64, v57, 1.0
	v_mul_f32_e32 v28, v28, v57
	v_mul_f32_e32 v29, v29, v57
	v_mul_f32_e32 v30, v30, v57
	v_mul_f32_e32 v31, v31, v57
	v_cvt_pk_bf16_f32 v28, v28, v29
	v_cvt_pk_bf16_f32 v29, v30, v31
	global_store_dwordx2 v[20:21], v[28:29], off
	v_lshl_add_u64 v[20:21], v[20:21], 0, s[10:11]
	v_div_scale_f32 v64, s[16:17], v58, v58, 1.0
	v_rcp_f32_e32 v65, v64
	v_div_scale_f32 v66, vcc, 1.0, v58, 1.0
	v_fma_f32 v67, -v64, v65, 1.0
	v_fmac_f32_e32 v65, v67, v65
	v_mul_f32_e32 v67, v66, v65
	v_fma_f32 v68, -v64, v67, v66
	v_fmac_f32_e32 v67, v68, v65
	v_fma_f32 v64, -v64, v67, v66
	v_div_fmas_f32 v64, v64, v65, v67
	v_div_fixup_f32 v58, v64, v58, 1.0
	v_mul_f32_e32 v32, v32, v58
	v_mul_f32_e32 v33, v33, v58
	v_mul_f32_e32 v34, v34, v58
	v_mul_f32_e32 v35, v35, v58
	v_cvt_pk_bf16_f32 v32, v32, v33
	v_cvt_pk_bf16_f32 v33, v34, v35
	global_store_dwordx2 v[20:21], v[32:33], off
	v_lshl_add_u64 v[20:21], v[20:21], 0, s[10:11]
	v_div_scale_f32 v64, s[16:17], v59, v59, 1.0
	v_rcp_f32_e32 v65, v64
	v_div_scale_f32 v66, vcc, 1.0, v59, 1.0
	v_fma_f32 v67, -v64, v65, 1.0
	v_fmac_f32_e32 v65, v67, v65
	v_mul_f32_e32 v67, v66, v65
	v_fma_f32 v68, -v64, v67, v66
	v_fmac_f32_e32 v67, v68, v65
	v_fma_f32 v64, -v64, v67, v66
	v_div_fmas_f32 v64, v64, v65, v67
	v_div_fixup_f32 v59, v64, v59, 1.0
	v_mul_f32_e32 v36, v36, v59
	v_mul_f32_e32 v37, v37, v59
	v_mul_f32_e32 v38, v38, v59
	v_mul_f32_e32 v39, v39, v59
	v_cvt_pk_bf16_f32 v36, v36, v37
	v_cvt_pk_bf16_f32 v37, v38, v39
	global_store_dwordx2 v[20:21], v[36:37], off
	v_lshl_add_u64 v[20:21], v[20:21], 0, s[10:11]
	s_waitcnt vmcnt(4)
	v_max_f32_e32 v56, v43, v43
	v_max_f32_e32 v60, v42, v42
	v_max_f32_e32 v56, v60, v56
	v_max3_f32 v56, v40, v41, v56
	v_max_f32_e32 v57, v47, v47
	v_max_f32_e32 v61, v46, v46
	v_max_f32_e32 v57, v61, v57
	v_max3_f32 v57, v44, v45, v57
	v_max_f32_e32 v58, v51, v51
	v_max_f32_e32 v62, v50, v50
	v_max_f32_e32 v58, v62, v58
	v_max3_f32 v58, v48, v49, v58
	v_max_f32_e32 v59, v55, v55
	v_max_f32_e32 v63, v54, v54
	v_max_f32_e32 v59, v63, v59
	v_max3_f32 v59, v52, v53, v59
	ds_bpermute_b32 v60, v8, v56
	ds_bpermute_b32 v61, v8, v57
	ds_bpermute_b32 v62, v8, v58
	ds_bpermute_b32 v63, v8, v59
	s_waitcnt lgkmcnt(3)
	v_max_f32_e32 v60, v60, v60
	v_max_f32_e32 v56, v56, v60
	s_waitcnt lgkmcnt(2)
	v_max_f32_e32 v61, v61, v61
	v_max_f32_e32 v57, v57, v61
	s_waitcnt lgkmcnt(1)
	v_max_f32_e32 v62, v62, v62
	v_max_f32_e32 v58, v58, v62
	s_waitcnt lgkmcnt(0)
	v_max_f32_e32 v63, v63, v63
	v_max_f32_e32 v59, v59, v63
	ds_bpermute_b32 v60, v9, v56
	ds_bpermute_b32 v61, v9, v57
	ds_bpermute_b32 v62, v9, v58
	ds_bpermute_b32 v63, v9, v59
	s_waitcnt lgkmcnt(3)
	v_max_f32_e32 v60, v60, v60
	v_max_f32_e32 v56, v56, v60
	s_waitcnt lgkmcnt(2)
	v_max_f32_e32 v61, v61, v61
	v_max_f32_e32 v57, v57, v61
	s_waitcnt lgkmcnt(1)
; DEV void store_bf4(bf16_t* p, f32x4 v) { uint2 w; w.x = cvt_pk_bf16(v[0], v[1]); w.y = cvt_pk_bf16(v[2], v[3]); *(uint2*)p = w; }
; DEV float wave_sum(float v) {
; #pragma unroll
;     for (int o = 32; o >= 1; o >>= 1) v += __shfl_xor(v, o);
;     return v;
; }
; DEV float wave_max(float v) {
; #pragma unroll
;     for (int o = 32; o >= 1; o >>= 1) v = fmaxf(v, __shfl_xor(v, o));
;     return v;
; }
; __global__ void __launch_bounds__(512) hymba_fwd(Params p) {
;     ...
;     for (int r = bid * 8 + wid; r < TP * 4; r += G * 8) {
;         const f32x4 v = __builtin_nontemporal_load((const f32x4*)(sc + (size_t)r * 256 + lane * 4));
;         const float mx = wave_max(fmaxf(fmaxf(v[0], v[1]), fmaxf(v[2], v[3])));
;         f32x4 e; e[0] = __expf(v[0] - mx); e[1] = __expf(v[1] - mx); e[2] = __expf(v[2] - mx); e[3] = __expf(v[3] - mx);
;         const float inv = 1.f / wave_sum(e[0] + e[1] + e[2] + e[3]);
;         store_bf4(pb + (size_t)(r >> 2) * LDP + (r & 3) * 256 + lane * 4, e * inv);
	v_max_f32_e32 v62, v62, v62
	v_max_f32_e32 v58, v58, v62
	s_waitcnt lgkmcnt(0)
	v_max_f32_e32 v63, v63, v63
	v_max_f32_e32 v59, v59, v63
	ds_bpermute_b32 v60, v10, v56
	ds_bpermute_b32 v61, v10, v57
	ds_bpermute_b32 v62, v10, v58
	ds_bpermute_b32 v63, v10, v59
	s_waitcnt lgkmcnt(3)
	v_max_f32_e32 v60, v60, v60
	v_max_f32_e32 v56, v56, v60
	s_waitcnt lgkmcnt(2)
	v_max_f32_e32 v61, v61, v61
	v_max_f32_e32 v57, v57, v61
	s_waitcnt lgkmcnt(1)
	v_max_f32_e32 v62, v62, v62
	v_max_f32_e32 v58, v58, v62
	s_waitcnt lgkmcnt(0)
	v_max_f32_e32 v63, v63, v63
	v_max_f32_e32 v59, v59, v63
	ds_bpermute_b32 v60, v11, v56
	ds_bpermute_b32 v61, v11, v57
	ds_bpermute_b32 v62, v11, v58
	ds_bpermute_b32 v63, v11, v59
	s_waitcnt lgkmcnt(3)
	v_max_f32_e32 v60, v60, v60
	v_max_f32_e32 v56, v56, v60
	s_waitcnt lgkmcnt(2)
	v_max_f32_e32 v61, v61, v61
	v_max_f32_e32 v57, v57, v61
	s_waitcnt lgkmcnt(1)
	v_max_f32_e32 v62, v62, v62
	v_max_f32_e32 v58, v58, v62
	s_waitcnt lgkmcnt(0)
	v_max_f32_e32 v63, v63, v63
	v_max_f32_e32 v59, v59, v63
	ds_bpermute_b32 v60, v12, v56
	ds_bpermute_b32 v61, v12, v57
	ds_bpermute_b32 v62, v12, v58
	ds_bpermute_b32 v63, v12, v59
	s_waitcnt lgkmcnt(3)
	v_max_f32_e32 v60, v60, v60
	v_max_f32_e32 v56, v56, v60
	s_waitcnt lgkmcnt(2)
	v_max_f32_e32 v61, v61, v61
	v_max_f32_e32 v57, v57, v61
	s_waitcnt lgkmcnt(1)
	v_max_f32_e32 v62, v62, v62
	v_max_f32_e32 v58, v58, v62
	s_waitcnt lgkmcnt(0)
	v_max_f32_e32 v63, v63, v63
	v_max_f32_e32 v59, v59, v63
	ds_bpermute_b32 v60, v13, v56
	ds_bpermute_b32 v61, v13, v57
	ds_bpermute_b32 v62, v13, v58
	ds_bpermute_b32 v63, v13, v59
	s_waitcnt lgkmcnt(3)
	v_max_f32_e32 v60, v60, v60
	v_max_f32_e32 v56, v56, v60
	s_waitcnt lgkmcnt(2)
	v_max_f32_e32 v61, v61, v61
	v_max_f32_e32 v57, v57, v61
	s_waitcnt lgkmcnt(1)
	v_max_f32_e32 v62, v62, v62
	v_max_f32_e32 v58, v58, v62
	s_waitcnt lgkmcnt(0)
	v_max_f32_e32 v63, v63, v63
	v_max_f32_e32 v59, v59, v63
	v_sub_f32_e32 v40, v40, v56
	v_sub_f32_e32 v41, v41, v56
	v_sub_f32_e32 v42, v42, v56
	v_sub_f32_e32 v43, v43, v56
	v_mul_f32_e32 v40, 0x3fb8aa3b, v40
	v_mul_f32_e32 v41, 0x3fb8aa3b, v41
	v_mul_f32_e32 v42, 0x3fb8aa3b, v42
	v_mul_f32_e32 v43, 0x3fb8aa3b, v43
	v_sub_f32_e32 v44, v44, v57
	v_sub_f32_e32 v45, v45, v57
	v_sub_f32_e32 v46, v46, v57
	v_sub_f32_e32 v47, v47, v57
	v_mul_f32_e32 v44, 0x3fb8aa3b, v44
	v_mul_f32_e32 v45, 0x3fb8aa3b, v45
	v_mul_f32_e32 v46, 0x3fb8aa3b, v46
	v_mul_f32_e32 v47, 0x3fb8aa3b, v47
	v_sub_f32_e32 v48, v48, v58
	v_sub_f32_e32 v49, v49, v58
	v_sub_f32_e32 v50, v50, v58
	v_sub_f32_e32 v51, v51, v58
	v_mul_f32_e32 v48, 0x3fb8aa3b, v48
	v_mul_f32_e32 v49, 0x3fb8aa3b, v49
	v_mul_f32_e32 v50, 0x3fb8aa3b, v50
	v_mul_f32_e32 v51, 0x3fb8aa3b, v51
	v_sub_f32_e32 v52, v52, v59
	v_sub_f32_e32 v53, v53, v59
	v_sub_f32_e32 v54, v54, v59
	v_sub_f32_e32 v55, v55, v59
	v_mul_f32_e32 v52, 0x3fb8aa3b, v52
	v_mul_f32_e32 v53, 0x3fb8aa3b, v53
	v_mul_f32_e32 v54, 0x3fb8aa3b, v54
	v_mul_f32_e32 v55, 0x3fb8aa3b, v55
	v_exp_f32_e32 v40, v40
	v_exp_f32_e32 v41, v41
	v_exp_f32_e32 v42, v42
	v_exp_f32_e32 v43, v43
	v_exp_f32_e32 v44, v44
	v_exp_f32_e32 v45, v45
	v_exp_f32_e32 v46, v46
	v_exp_f32_e32 v47, v47
	v_exp_f32_e32 v48, v48
	v_exp_f32_e32 v49, v49
	v_exp_f32_e32 v50, v50
	v_exp_f32_e32 v51, v51
	v_exp_f32_e32 v52, v52
	v_exp_f32_e32 v53, v53
	v_exp_f32_e32 v54, v54
	v_exp_f32_e32 v55, v55
	v_add_f32_e32 v56, v40, v41
	v_add_f32_e32 v56, v42, v56
	v_add_f32_e32 v56, v43, v56
	v_add_f32_e32 v57, v44, v45
	v_add_f32_e32 v57, v46, v57
	v_add_f32_e32 v57, v47, v57
	v_add_f32_e32 v58, v48, v49
	v_add_f32_e32 v58, v50, v58
	v_add_f32_e32 v58, v51, v58
	v_add_f32_e32 v59, v52, v53
	v_add_f32_e32 v59, v54, v59
	v_add_f32_e32 v59, v55, v59
	ds_bpermute_b32 v60, v8, v56
	ds_bpermute_b32 v61, v8, v57
	ds_bpermute_b32 v62, v8, v58
	ds_bpermute_b32 v63, v8, v59
	s_waitcnt lgkmcnt(3)
	v_add_f32_e32 v56, v56, v60
	s_waitcnt lgkmcnt(2)
	v_add_f32_e32 v57, v57, v61
	s_waitcnt lgkmcnt(1)
	v_add_f32_e32 v58, v58, v62
	s_waitcnt lgkmcnt(0)
	v_add_f32_e32 v59, v59, v63
	ds_bpermute_b32 v60, v9, v56
	ds_bpermute_b32 v61, v9, v57
	ds_bpermute_b32 v62, v9, v58
	ds_bpermute_b32 v63, v9, v59
	s_waitcnt lgkmcnt(3)
; DEV void store_bf4(bf16_t* p, f32x4 v) { uint2 w; w.x = cvt_pk_bf16(v[0], v[1]); w.y = cvt_pk_bf16(v[2], v[3]); *(uint2*)p = w; }
; DEV float wave_sum(float v) {
; #pragma unroll
;     for (int o = 32; o >= 1; o >>= 1) v += __shfl_xor(v, o);
;     return v;
; }
; DEV float wave_max(float v) {
; #pragma unroll
;     for (int o = 32; o >= 1; o >>= 1) v = fmaxf(v, __shfl_xor(v, o));
;     return v;
; }
; __global__ void __launch_bounds__(512) hymba_fwd(Params p) {
;     ...
;     for (int r = bid * 8 + wid; r < TP * 4; r += G * 8) {
;         const f32x4 v = __builtin_nontemporal_load((const f32x4*)(sc + (size_t)r * 256 + lane * 4));
;         const float mx = wave_max(fmaxf(fmaxf(v[0], v[1]), fmaxf(v[2], v[3])));
;         f32x4 e; e[0] = __expf(v[0] - mx); e[1] = __expf(v[1] - mx); e[2] = __expf(v[2] - mx); e[3] = __expf(v[3] - mx);
;         const float inv = 1.f / wave_sum(e[0] + e[1] + e[2] + e[3]);
;         store_bf4(pb + (size_t)(r >> 2) * LDP + (r & 3) * 256 + lane * 4, e * inv);
	v_add_f32_e32 v56, v56, v60
	s_waitcnt lgkmcnt(2)
	v_add_f32_e32 v57, v57, v61
	s_waitcnt lgkmcnt(1)
	v_add_f32_e32 v58, v58, v62
	s_waitcnt lgkmcnt(0)
	v_add_f32_e32 v59, v59, v63
	ds_bpermute_b32 v60, v10, v56
	ds_bpermute_b32 v61, v10, v57
	ds_bpermute_b32 v62, v10, v58
	ds_bpermute_b32 v63, v10, v59
	s_waitcnt lgkmcnt(3)
	v_add_f32_e32 v56, v56, v60
	s_waitcnt lgkmcnt(2)
	v_add_f32_e32 v57, v57, v61
	s_waitcnt lgkmcnt(1)
	v_add_f32_e32 v58, v58, v62
	s_waitcnt lgkmcnt(0)
	v_add_f32_e32 v59, v59, v63
	ds_bpermute_b32 v60, v11, v56
	ds_bpermute_b32 v61, v11, v57
	ds_bpermute_b32 v62, v11, v58
	ds_bpermute_b32 v63, v11, v59
	s_waitcnt lgkmcnt(3)
	v_add_f32_e32 v56, v56, v60
	s_waitcnt lgkmcnt(2)
	v_add_f32_e32 v57, v57, v61
	s_waitcnt lgkmcnt(1)
	v_add_f32_e32 v58, v58, v62
	s_waitcnt lgkmcnt(0)
	v_add_f32_e32 v59, v59, v63
	ds_bpermute_b32 v60, v12, v56
	ds_bpermute_b32 v61, v12, v57
	ds_bpermute_b32 v62, v12, v58
	ds_bpermute_b32 v63, v12, v59
	s_waitcnt lgkmcnt(3)
	v_add_f32_e32 v56, v56, v60
	s_waitcnt lgkmcnt(2)
	v_add_f32_e32 v57, v57, v61
	s_waitcnt lgkmcnt(1)
	v_add_f32_e32 v58, v58, v62
	s_waitcnt lgkmcnt(0)
	v_add_f32_e32 v59, v59, v63
	ds_bpermute_b32 v60, v13, v56
	ds_bpermute_b32 v61, v13, v57
	ds_bpermute_b32 v62, v13, v58
	ds_bpermute_b32 v63, v13, v59
	s_waitcnt lgkmcnt(3)
	v_add_f32_e32 v56, v56, v60
	s_waitcnt lgkmcnt(2)
	v_add_f32_e32 v57, v57, v61
	s_waitcnt lgkmcnt(1)
	v_add_f32_e32 v58, v58, v62
	s_waitcnt lgkmcnt(0)
	v_add_f32_e32 v59, v59, v63
	v_div_scale_f32 v64, s[16:17], v56, v56, 1.0
	v_rcp_f32_e32 v65, v64
	v_div_scale_f32 v66, vcc, 1.0, v56, 1.0
	v_fma_f32 v67, -v64, v65, 1.0
	v_fmac_f32_e32 v65, v67, v65
	v_mul_f32_e32 v67, v66, v65
	v_fma_f32 v68, -v64, v67, v66
	v_fmac_f32_e32 v67, v68, v65
	v_fma_f32 v64, -v64, v67, v66
	v_div_fmas_f32 v64, v64, v65, v67
	v_div_fixup_f32 v56, v64, v56, 1.0
	v_mul_f32_e32 v40, v40, v56
	v_mul_f32_e32 v41, v41, v56
	v_mul_f32_e32 v42, v42, v56
	v_mul_f32_e32 v43, v43, v56
	v_cvt_pk_bf16_f32 v40, v40, v41
	v_cvt_pk_bf16_f32 v41, v42, v43
	global_store_dwordx2 v[20:21], v[40:41], off
	v_lshl_add_u64 v[20:21], v[20:21], 0, s[10:11]
	v_div_scale_f32 v64, s[16:17], v57, v57, 1.0
	v_rcp_f32_e32 v65, v64
	v_div_scale_f32 v66, vcc, 1.0, v57, 1.0
	v_fma_f32 v67, -v64, v65, 1.0
	v_fmac_f32_e32 v65, v67, v65
	v_mul_f32_e32 v67, v66, v65
	v_fma_f32 v68, -v64, v67, v66
	v_fmac_f32_e32 v67, v68, v65
	v_fma_f32 v64, -v64, v67, v66
	v_div_fmas_f32 v64, v64, v65, v67
	v_div_fixup_f32 v57, v64, v57, 1.0
	v_mul_f32_e32 v44, v44, v57
	v_mul_f32_e32 v45, v45, v57
	v_mul_f32_e32 v46, v46, v57
	v_mul_f32_e32 v47, v47, v57
	v_cvt_pk_bf16_f32 v44, v44, v45
	v_cvt_pk_bf16_f32 v45, v46, v47
	global_store_dwordx2 v[20:21], v[44:45], off
	v_lshl_add_u64 v[20:21], v[20:21], 0, s[10:11]
	v_div_scale_f32 v64, s[16:17], v58, v58, 1.0
	v_rcp_f32_e32 v65, v64
	v_div_scale_f32 v66, vcc, 1.0, v58, 1.0
	v_fma_f32 v67, -v64, v65, 1.0
	v_fmac_f32_e32 v65, v67, v65
	v_mul_f32_e32 v67, v66, v65
	v_fma_f32 v68, -v64, v67, v66
	v_fmac_f32_e32 v67, v68, v65
	v_fma_f32 v64, -v64, v67, v66
	v_div_fmas_f32 v64, v64, v65, v67
	v_div_fixup_f32 v58, v64, v58, 1.0
	v_mul_f32_e32 v48, v48, v58
	v_mul_f32_e32 v49, v49, v58
	v_mul_f32_e32 v50, v50, v58
	v_mul_f32_e32 v51, v51, v58
	v_cvt_pk_bf16_f32 v48, v48, v49
	v_cvt_pk_bf16_f32 v49, v50, v51
	global_store_dwordx2 v[20:21], v[48:49], off
	v_lshl_add_u64 v[20:21], v[20:21], 0, s[10:11]
	v_div_scale_f32 v64, s[16:17], v59, v59, 1.0
	v_rcp_f32_e32 v65, v64
	v_div_scale_f32 v66, vcc, 1.0, v59, 1.0
	v_fma_f32 v67, -v64, v65, 1.0
	v_fmac_f32_e32 v65, v67, v65
	v_mul_f32_e32 v67, v66, v65
	v_fma_f32 v68, -v64, v67, v66
	v_fmac_f32_e32 v67, v68, v65
	v_fma_f32 v64, -v64, v67, v66
	v_div_fmas_f32 v64, v64, v65, v67
	v_div_fixup_f32 v59, v64, v59, 1.0
	v_mul_f32_e32 v52, v52, v59
	v_mul_f32_e32 v53, v53, v59
	v_mul_f32_e32 v54, v54, v59
	v_mul_f32_e32 v55, v55, v59
	v_cvt_pk_bf16_f32 v52, v52, v53
	v_cvt_pk_bf16_f32 v53, v54, v55
	global_store_dwordx2 v[20:21], v[52:53], off
	v_lshl_add_u64 v[20:21], v[20:21], 0, s[10:11]
	s_branch .LBB0_1353
